# v3 plus K-loop heads on 64-byte boundaries and all dense MFMA runs 8-byte aligned (s_nop pads)
# speedup vs baseline: 1.0005x; 1.0005x over previous
.LBB0_185:
	s_ashr_i32 s53, s52, 31
	s_lshl_b64 s[4:5], s[52:53], 19
	s_add_u32 s54, s3, s4
	s_addc_u32 s55, s45, s5
	s_and_b64 s[4:5], s[8:9], exec
	s_cselect_b32 s4, s55, s61
	s_cselect_b32 s5, s54, s60
	s_ashr_i32 s43, s42, 31
	s_lshl_b64 s[46:47], s[42:43], 19
	s_add_u32 s56, s66, s46
	s_addc_u32 s57, s67, s47
	s_and_b64 s[46:47], s[8:9], exec
	s_cselect_b32 s11, s57, s63
	s_cselect_b32 s35, s56, s62
	s_add_u32 s60, s60, 0x40080
	s_addc_u32 s61, s61, 0
	s_add_u32 s43, s62, 0x100
	v_mov_b32_e32 v0, 0
	s_addc_u32 s48, s63, 0
	s_mov_b32 s49, -2
	v_mov_b32_e32 v1, v0
	v_mov_b32_e32 v2, v0
	v_mov_b32_e32 v3, v0
	v_mov_b32_e32 v4, v0
	v_mov_b32_e32 v5, v0
	v_mov_b32_e32 v6, v0
	v_mov_b32_e32 v7, v0
	v_mov_b32_e32 v8, v0
	v_mov_b32_e32 v9, v0
	v_mov_b32_e32 v10, v0
	v_mov_b32_e32 v11, v0
	v_mov_b32_e32 v12, v0
	v_mov_b32_e32 v13, v0
	v_mov_b32_e32 v14, v0
	v_mov_b32_e32 v15, v0
	v_mov_b32_e32 v16, v0
	v_mov_b32_e32 v17, v0
	v_mov_b32_e32 v18, v0
	v_mov_b32_e32 v19, v0
	v_mov_b32_e32 v20, v0
	v_mov_b32_e32 v21, v0
	v_mov_b32_e32 v22, v0
	v_mov_b32_e32 v23, v0
	v_mov_b32_e32 v24, v0
	v_mov_b32_e32 v25, v0
	v_mov_b32_e32 v26, v0
	v_mov_b32_e32 v27, v0
	v_mov_b32_e32 v28, v0
	v_mov_b32_e32 v29, v0
	v_mov_b32_e32 v30, v0
	v_mov_b32_e32 v31, v0
	v_mov_b32_e32 v64, v0
	v_mov_b32_e32 v65, v0
	v_mov_b32_e32 v66, v0
	v_mov_b32_e32 v67, v0
	v_mov_b32_e32 v68, v0
	v_mov_b32_e32 v69, v0
	v_mov_b32_e32 v70, v0
	v_mov_b32_e32 v71, v0
	v_mov_b32_e32 v72, v0
	v_mov_b32_e32 v73, v0
	v_mov_b32_e32 v74, v0
	v_mov_b32_e32 v75, v0
	v_mov_b32_e32 v76, v0
	v_mov_b32_e32 v77, v0
	v_mov_b32_e32 v78, v0
	v_mov_b32_e32 v79, v0
	v_mov_b32_e32 v80, v0
	v_mov_b32_e32 v81, v0
	v_mov_b32_e32 v82, v0
	v_mov_b32_e32 v83, v0
	v_mov_b32_e32 v84, v0
	v_mov_b32_e32 v85, v0
	v_mov_b32_e32 v86, v0
	v_mov_b32_e32 v87, v0
	v_mov_b32_e32 v88, v0
	v_mov_b32_e32 v89, v0
	v_mov_b32_e32 v90, v0
	v_mov_b32_e32 v91, v0
	v_mov_b32_e32 v92, v0
	v_mov_b32_e32 v93, v0
	v_mov_b32_e32 v94, v0
	v_mov_b32_e32 v95, v0
	v_mov_b32_e32 v32, v0
	v_mov_b32_e32 v33, v0
	v_mov_b32_e32 v34, v0
	v_mov_b32_e32 v35, v0
	v_mov_b32_e32 v36, v0
	v_mov_b32_e32 v37, v0
	v_mov_b32_e32 v38, v0
	v_mov_b32_e32 v39, v0
	v_mov_b32_e32 v40, v0
	v_mov_b32_e32 v41, v0
	v_mov_b32_e32 v42, v0
	v_mov_b32_e32 v43, v0
	v_mov_b32_e32 v44, v0
	v_mov_b32_e32 v45, v0
	v_mov_b32_e32 v46, v0
	v_mov_b32_e32 v47, v0
	v_mov_b32_e32 v48, v0
	v_mov_b32_e32 v49, v0
	v_mov_b32_e32 v50, v0
	v_mov_b32_e32 v51, v0
	v_mov_b32_e32 v52, v0
	v_mov_b32_e32 v53, v0
	v_mov_b32_e32 v54, v0
	v_mov_b32_e32 v55, v0
	v_mov_b32_e32 v56, v0
	v_mov_b32_e32 v57, v0
	v_mov_b32_e32 v58, v0
	v_mov_b32_e32 v59, v0
	v_mov_b32_e32 v60, v0
	v_mov_b32_e32 v61, v0
	v_mov_b32_e32 v62, v0
	v_mov_b32_e32 v63, v0
	v_mov_b32_e32 v96, v0
	v_mov_b32_e32 v97, v0
	v_mov_b32_e32 v98, v0
	v_mov_b32_e32 v99, v0
	v_mov_b32_e32 v100, v0
	v_mov_b32_e32 v101, v0
	v_mov_b32_e32 v102, v0
	v_mov_b32_e32 v103, v0
	v_mov_b32_e32 v104, v0
	v_mov_b32_e32 v105, v0
	v_mov_b32_e32 v106, v0
	v_mov_b32_e32 v107, v0
	v_mov_b32_e32 v108, v0
	v_mov_b32_e32 v109, v0
	v_mov_b32_e32 v110, v0
	v_mov_b32_e32 v111, v0
	v_mov_b32_e32 v112, v0
	v_mov_b32_e32 v113, v0
	v_mov_b32_e32 v114, v0
	v_mov_b32_e32 v115, v0
	v_mov_b32_e32 v116, v0
	v_mov_b32_e32 v117, v0
	v_mov_b32_e32 v118, v0
	v_mov_b32_e32 v119, v0
	v_mov_b32_e32 v120, v0
	v_mov_b32_e32 v121, v0
	v_mov_b32_e32 v122, v0
	v_mov_b32_e32 v123, v0
	v_mov_b32_e32 v124, v0
	v_mov_b32_e32 v125, v0
	v_mov_b32_e32 v126, v0
	v_mov_b32_e32 v127, v0
	s_nop 0
	s_nop 0
	s_nop 0
	s_nop 0
	s_nop 0
	s_nop 0
	s_nop 0
.LBB0_186:
	v_add_u32_e32 v140, s82, v198
	v_add_u32_e32 v160, s83, v198
	ds_read_b128 v[128:131], v140
	ds_read_b128 v[132:135], v140 offset:1024
	ds_read_b128 v[136:139], v140 offset:2048
	ds_read_b128 v[140:143], v140 offset:3072
	ds_read_b128 v[144:147], v160
	ds_read_b128 v[148:151], v160 offset:1024
	ds_read_b128 v[184:187], v160 offset:2048
	ds_read_b128 v[188:191], v160 offset:3072
	s_add_u32 s46, s60, 0xfffc0080
	s_addc_u32 s47, s61, -1
	s_cmp_eq_u32 s49, 12
	s_cselect_b32 s65, s4, s47
	s_cselect_b32 s64, s5, s46
	s_cselect_b32 s63, s11, s48
	s_cselect_b32 s62, s35, s43
	v_lshl_add_u64 v[252:253], s[60:61], 0, v[174:175]
	s_add_i32 m0, s69, 0xc000
	ds_read_b128 v[220:223], v209
	ds_read_b128 v[224:227], v209 offset:1024
	ds_read_b128 v[228:231], v209 offset:2048
	ds_read_b128 v[232:235], v209 offset:3072
	ds_read_b128 v[236:239], v209 offset:4096
	ds_read_b128 v[240:243], v209 offset:5120
	ds_read_b128 v[244:247], v209 offset:6144
	ds_read_b128 v[248:251], v209 offset:7168
	global_load_lds_dwordx4 v[252:253], off
	v_lshl_add_u64 v[252:253], s[60:61], 0, v[176:177]
	s_add_i32 m0, s69, 0xe000
	s_nop 0
	global_load_lds_dwordx4 v[252:253], off
	s_waitcnt vmcnt(8)
	s_waitcnt lgkmcnt(0)
	s_barrier
	s_setprio 1
	s_waitcnt lgkmcnt(0)
	v_mfma_f32_16x16x32_bf16 v[124:127], v[128:131], v[220:223], v[124:127]
	v_mfma_f32_16x16x32_bf16 v[120:123], v[136:139], v[220:223], v[120:123]
	v_mfma_f32_16x16x32_bf16 v[116:119], v[128:131], v[228:231], v[116:119]
	v_mfma_f32_16x16x32_bf16 v[112:115], v[136:139], v[228:231], v[112:115]
	v_mfma_f32_16x16x32_bf16 v[108:111], v[128:131], v[236:239], v[108:111]
	v_mfma_f32_16x16x32_bf16 v[104:107], v[136:139], v[236:239], v[104:107]
	v_mfma_f32_16x16x32_bf16 v[100:103], v[128:131], v[244:247], v[100:103]
	v_mfma_f32_16x16x32_bf16 v[96:99], v[136:139], v[244:247], v[96:99]
	v_mfma_f32_16x16x32_bf16 v[124:127], v[132:135], v[224:227], v[124:127]
	v_mfma_f32_16x16x32_bf16 v[120:123], v[140:143], v[224:227], v[120:123]
	v_mfma_f32_16x16x32_bf16 v[116:119], v[132:135], v[232:235], v[116:119]
	v_mfma_f32_16x16x32_bf16 v[112:115], v[140:143], v[232:235], v[112:115]
	v_mfma_f32_16x16x32_bf16 v[108:111], v[132:135], v[240:243], v[108:111]
	v_mfma_f32_16x16x32_bf16 v[104:107], v[140:143], v[240:243], v[104:107]
	v_mfma_f32_16x16x32_bf16 v[100:103], v[132:135], v[248:251], v[100:103]
	v_mfma_f32_16x16x32_bf16 v[96:99], v[140:143], v[248:251], v[96:99]
	s_setprio 0
	s_setprio 1
	v_mfma_f32_16x16x32_bf16 v[60:63], v[144:147], v[220:223], v[60:63]
	v_mfma_f32_16x16x32_bf16 v[56:59], v[184:187], v[220:223], v[56:59]
	v_mfma_f32_16x16x32_bf16 v[52:55], v[144:147], v[228:231], v[52:55]
	v_mfma_f32_16x16x32_bf16 v[48:51], v[184:187], v[228:231], v[48:51]
	v_mfma_f32_16x16x32_bf16 v[44:47], v[144:147], v[236:239], v[44:47]
	v_mfma_f32_16x16x32_bf16 v[40:43], v[184:187], v[236:239], v[40:43]
	v_mfma_f32_16x16x32_bf16 v[36:39], v[144:147], v[244:247], v[36:39]
	v_mfma_f32_16x16x32_bf16 v[32:35], v[184:187], v[244:247], v[32:35]
	v_mfma_f32_16x16x32_bf16 v[60:63], v[148:151], v[224:227], v[60:63]
	v_mfma_f32_16x16x32_bf16 v[56:59], v[188:191], v[224:227], v[56:59]
	v_mfma_f32_16x16x32_bf16 v[52:55], v[148:151], v[232:235], v[52:55]
	v_mfma_f32_16x16x32_bf16 v[48:51], v[188:191], v[232:235], v[48:51]
	v_mfma_f32_16x16x32_bf16 v[44:47], v[148:151], v[240:243], v[44:47]
	v_mfma_f32_16x16x32_bf16 v[40:43], v[188:191], v[240:243], v[40:43]
	v_mfma_f32_16x16x32_bf16 v[36:39], v[148:151], v[248:251], v[36:39]
	v_mfma_f32_16x16x32_bf16 v[32:35], v[188:191], v[248:251], v[32:35]
	s_setprio 0
	s_barrier
	s_add_i32 s46, s82, s68
	v_lshl_add_u64 v[252:253], s[62:63], 0, v[154:155]
	s_mov_b32 m0, s46
	ds_read_b128 v[220:223], v209 offset:16384
	ds_read_b128 v[224:227], v209 offset:17408
	ds_read_b128 v[228:231], v209 offset:18432
	ds_read_b128 v[232:235], v209 offset:19456
	ds_read_b128 v[236:239], v209 offset:20480
	ds_read_b128 v[240:243], v209 offset:21504
	ds_read_b128 v[244:247], v209 offset:22528
	ds_read_b128 v[248:251], v209 offset:23552
	global_load_lds_dwordx4 v[252:253], off
	s_add_i32 m0, s46, 0x2000
	s_add_u32 s46, s62, 0x40000
	v_lshl_add_u64 v[202:203], s[62:63], 0, v[158:159]
	s_addc_u32 s47, s63, 0
	s_add_i32 s50, s83, s68
	global_load_lds_dwordx4 v[202:203], off
	v_lshl_add_u64 v[204:205], s[46:47], 0, v[154:155]
	s_mov_b32 m0, s50
	v_lshl_add_u64 v[206:207], s[64:65], 0, v[156:157]
	global_load_lds_dwordx4 v[204:205], off
	v_lshl_add_u64 v[204:205], s[46:47], 0, v[158:159]
	s_add_i32 m0, s50, 0x2000
	s_nop 0
	global_load_lds_dwordx4 v[204:205], off
	v_lshl_add_u64 v[204:205], s[64:65], 0, v[152:153]
	s_mov_b32 m0, s69
	s_nop 0
	global_load_lds_dwordx4 v[204:205], off
	s_mov_b32 m0, s70
	s_nop 0
	global_load_lds_dwordx4 v[206:207], off
	s_nop 0
	s_waitcnt vmcnt(8)
	s_waitcnt lgkmcnt(0)
	s_barrier
	s_setprio 1
	s_waitcnt lgkmcnt(0)
	v_mfma_f32_16x16x32_bf16 v[92:95], v[128:131], v[220:223], v[92:95]
	v_mfma_f32_16x16x32_bf16 v[88:91], v[136:139], v[220:223], v[88:91]
	v_mfma_f32_16x16x32_bf16 v[84:87], v[128:131], v[228:231], v[84:87]
	v_mfma_f32_16x16x32_bf16 v[80:83], v[136:139], v[228:231], v[80:83]
	v_mfma_f32_16x16x32_bf16 v[76:79], v[128:131], v[236:239], v[76:79]
	v_mfma_f32_16x16x32_bf16 v[72:75], v[136:139], v[236:239], v[72:75]
	v_mfma_f32_16x16x32_bf16 v[68:71], v[128:131], v[244:247], v[68:71]
	v_mfma_f32_16x16x32_bf16 v[64:67], v[136:139], v[244:247], v[64:67]
	v_mfma_f32_16x16x32_bf16 v[92:95], v[132:135], v[224:227], v[92:95]
	v_mfma_f32_16x16x32_bf16 v[88:91], v[140:143], v[224:227], v[88:91]
	v_mfma_f32_16x16x32_bf16 v[84:87], v[132:135], v[232:235], v[84:87]
	v_mfma_f32_16x16x32_bf16 v[80:83], v[140:143], v[232:235], v[80:83]
	v_mfma_f32_16x16x32_bf16 v[76:79], v[132:135], v[240:243], v[76:79]
	v_mfma_f32_16x16x32_bf16 v[72:75], v[140:143], v[240:243], v[72:75]
	v_mfma_f32_16x16x32_bf16 v[68:71], v[132:135], v[248:251], v[68:71]
	v_mfma_f32_16x16x32_bf16 v[64:67], v[140:143], v[248:251], v[64:67]
	s_setprio 0
	s_setprio 1
	v_mfma_f32_16x16x32_bf16 v[28:31], v[144:147], v[220:223], v[28:31]
	v_mfma_f32_16x16x32_bf16 v[24:27], v[184:187], v[220:223], v[24:27]
	v_mfma_f32_16x16x32_bf16 v[20:23], v[144:147], v[228:231], v[20:23]
	v_mfma_f32_16x16x32_bf16 v[16:19], v[184:187], v[228:231], v[16:19]
	v_mfma_f32_16x16x32_bf16 v[12:15], v[144:147], v[236:239], v[12:15]
	v_mfma_f32_16x16x32_bf16 v[8:11], v[184:187], v[236:239], v[8:11]
	v_mfma_f32_16x16x32_bf16 v[4:7], v[144:147], v[244:247], v[4:7]
	v_mfma_f32_16x16x32_bf16 v[0:3], v[184:187], v[244:247], v[0:3]
	v_mfma_f32_16x16x32_bf16 v[28:31], v[148:151], v[224:227], v[28:31]
	v_mfma_f32_16x16x32_bf16 v[24:27], v[188:191], v[224:227], v[24:27]
	v_mfma_f32_16x16x32_bf16 v[20:23], v[148:151], v[232:235], v[20:23]
	v_mfma_f32_16x16x32_bf16 v[16:19], v[188:191], v[232:235], v[16:19]
	v_mfma_f32_16x16x32_bf16 v[12:15], v[148:151], v[240:243], v[12:15]
	v_mfma_f32_16x16x32_bf16 v[8:11], v[188:191], v[240:243], v[8:11]
	v_mfma_f32_16x16x32_bf16 v[4:7], v[148:151], v[248:251], v[4:7]
	v_mfma_f32_16x16x32_bf16 v[0:3], v[188:191], v[248:251], v[0:3]
	s_setprio 0
	s_barrier
	s_add_i32 s50, 0, 0x18000
	s_add_i32 s51, 0, 0x1c000
	v_add_u32_e32 v140, s50, v198
	v_add_u32_e32 v160, s51, v198
	ds_read_b128 v[128:131], v140
	ds_read_b128 v[132:135], v140 offset:1024
	ds_read_b128 v[136:139], v140 offset:2048
	ds_read_b128 v[140:143], v140 offset:3072
	ds_read_b128 v[144:147], v160
	ds_read_b128 v[148:151], v160 offset:1024
	ds_read_b128 v[184:187], v160 offset:2048
	ds_read_b128 v[188:191], v160 offset:3072
	s_add_u32 s46, s64, 0x40000
	s_addc_u32 s47, s65, 0
	s_mov_b32 m0, s71
	v_lshl_add_u64 v[212:213], s[46:47], 0, v[152:153]
	ds_read_b128 v[220:223], v209 offset:32768
	ds_read_b128 v[224:227], v209 offset:33792
	ds_read_b128 v[228:231], v209 offset:34816
	ds_read_b128 v[232:235], v209 offset:35840
	ds_read_b128 v[236:239], v209 offset:36864
	ds_read_b128 v[240:243], v209 offset:37888
	ds_read_b128 v[244:247], v209 offset:38912
	ds_read_b128 v[248:251], v209 offset:39936
	global_load_lds_dwordx4 v[212:213], off
	v_lshl_add_u64 v[212:213], s[46:47], 0, v[156:157]
	s_mov_b32 m0, s72
	s_nop 0
	global_load_lds_dwordx4 v[212:213], off
	s_nop 0
	s_waitcnt vmcnt(8)
	s_waitcnt lgkmcnt(0)
	s_barrier
	s_setprio 1
	s_waitcnt lgkmcnt(0)
	v_mfma_f32_16x16x32_bf16 v[124:127], v[128:131], v[220:223], v[124:127]
	v_mfma_f32_16x16x32_bf16 v[120:123], v[136:139], v[220:223], v[120:123]
	v_mfma_f32_16x16x32_bf16 v[116:119], v[128:131], v[228:231], v[116:119]
	v_mfma_f32_16x16x32_bf16 v[112:115], v[136:139], v[228:231], v[112:115]
	v_mfma_f32_16x16x32_bf16 v[108:111], v[128:131], v[236:239], v[108:111]
	v_mfma_f32_16x16x32_bf16 v[104:107], v[136:139], v[236:239], v[104:107]
	v_mfma_f32_16x16x32_bf16 v[100:103], v[128:131], v[244:247], v[100:103]
	v_mfma_f32_16x16x32_bf16 v[96:99], v[136:139], v[244:247], v[96:99]
	v_mfma_f32_16x16x32_bf16 v[124:127], v[132:135], v[224:227], v[124:127]
	v_mfma_f32_16x16x32_bf16 v[120:123], v[140:143], v[224:227], v[120:123]
	v_mfma_f32_16x16x32_bf16 v[116:119], v[132:135], v[232:235], v[116:119]
	v_mfma_f32_16x16x32_bf16 v[112:115], v[140:143], v[232:235], v[112:115]
	v_mfma_f32_16x16x32_bf16 v[108:111], v[132:135], v[240:243], v[108:111]
	v_mfma_f32_16x16x32_bf16 v[104:107], v[140:143], v[240:243], v[104:107]
	v_mfma_f32_16x16x32_bf16 v[100:103], v[132:135], v[248:251], v[100:103]
	v_mfma_f32_16x16x32_bf16 v[96:99], v[140:143], v[248:251], v[96:99]
	s_setprio 0
	s_setprio 1
	v_mfma_f32_16x16x32_bf16 v[60:63], v[144:147], v[220:223], v[60:63]
	v_mfma_f32_16x16x32_bf16 v[56:59], v[184:187], v[220:223], v[56:59]
	v_mfma_f32_16x16x32_bf16 v[52:55], v[144:147], v[228:231], v[52:55]
	v_mfma_f32_16x16x32_bf16 v[48:51], v[184:187], v[228:231], v[48:51]
	v_mfma_f32_16x16x32_bf16 v[44:47], v[144:147], v[236:239], v[44:47]
	v_mfma_f32_16x16x32_bf16 v[40:43], v[184:187], v[236:239], v[40:43]
	v_mfma_f32_16x16x32_bf16 v[36:39], v[144:147], v[244:247], v[36:39]
	v_mfma_f32_16x16x32_bf16 v[32:35], v[184:187], v[244:247], v[32:35]
	v_mfma_f32_16x16x32_bf16 v[60:63], v[148:151], v[224:227], v[60:63]
	v_mfma_f32_16x16x32_bf16 v[56:59], v[188:191], v[224:227], v[56:59]
	v_mfma_f32_16x16x32_bf16 v[52:55], v[148:151], v[232:235], v[52:55]
	v_mfma_f32_16x16x32_bf16 v[48:51], v[188:191], v[232:235], v[48:51]
	v_mfma_f32_16x16x32_bf16 v[44:47], v[148:151], v[240:243], v[44:47]
	v_mfma_f32_16x16x32_bf16 v[40:43], v[188:191], v[240:243], v[40:43]
	v_mfma_f32_16x16x32_bf16 v[36:39], v[148:151], v[248:251], v[36:39]
	v_mfma_f32_16x16x32_bf16 v[32:35], v[188:191], v[248:251], v[32:35]
	s_setprio 0
	s_barrier
	s_add_i32 s46, s50, s68
	v_lshl_add_u64 v[212:213], v[252:253], 0, s[16:17]
	s_mov_b32 m0, s46
	ds_read_b128 v[220:223], v209 offset:49152
	ds_read_b128 v[224:227], v209 offset:50176
	ds_read_b128 v[228:231], v209 offset:51200
	ds_read_b128 v[232:235], v209 offset:52224
	ds_read_b128 v[236:239], v209 offset:53248
	ds_read_b128 v[240:243], v209 offset:54272
	ds_read_b128 v[244:247], v209 offset:55296
	ds_read_b128 v[248:251], v209 offset:56320
	global_load_lds_dwordx4 v[212:213], off
	s_add_i32 m0, s46, 0x2000
	s_add_u32 s46, s62, 0x40080
	v_lshl_add_u64 v[202:203], v[202:203], 0, s[16:17]
	s_addc_u32 s47, s63, 0
	s_add_i32 s50, s51, s68
	global_load_lds_dwordx4 v[202:203], off
	v_lshl_add_u64 v[202:203], s[46:47], 0, v[154:155]
	s_mov_b32 m0, s50
	s_nop 0
	global_load_lds_dwordx4 v[202:203], off
	v_lshl_add_u64 v[202:203], s[46:47], 0, v[158:159]
	s_add_i32 m0, s50, 0x2000
	s_nop 0
	global_load_lds_dwordx4 v[202:203], off
	v_lshl_add_u64 v[202:203], v[204:205], 0, s[16:17]
	s_mov_b32 m0, s79
	s_nop 0
	global_load_lds_dwordx4 v[202:203], off
	v_lshl_add_u64 v[202:203], v[206:207], 0, s[16:17]
	s_mov_b32 m0, s80
	s_nop 0
	global_load_lds_dwordx4 v[202:203], off
	s_waitcnt vmcnt(8)
	s_waitcnt lgkmcnt(0)
	s_barrier
	s_setprio 1
	s_waitcnt lgkmcnt(0)
	v_mfma_f32_16x16x32_bf16 v[92:95], v[128:131], v[220:223], v[92:95]
	v_mfma_f32_16x16x32_bf16 v[88:91], v[136:139], v[220:223], v[88:91]
	v_mfma_f32_16x16x32_bf16 v[84:87], v[128:131], v[228:231], v[84:87]
	v_mfma_f32_16x16x32_bf16 v[80:83], v[136:139], v[228:231], v[80:83]
	v_mfma_f32_16x16x32_bf16 v[76:79], v[128:131], v[236:239], v[76:79]
	v_mfma_f32_16x16x32_bf16 v[72:75], v[136:139], v[236:239], v[72:75]
	v_mfma_f32_16x16x32_bf16 v[68:71], v[128:131], v[244:247], v[68:71]
	v_mfma_f32_16x16x32_bf16 v[64:67], v[136:139], v[244:247], v[64:67]
	v_mfma_f32_16x16x32_bf16 v[92:95], v[132:135], v[224:227], v[92:95]
	v_mfma_f32_16x16x32_bf16 v[88:91], v[140:143], v[224:227], v[88:91]
	v_mfma_f32_16x16x32_bf16 v[84:87], v[132:135], v[232:235], v[84:87]
	v_mfma_f32_16x16x32_bf16 v[80:83], v[140:143], v[232:235], v[80:83]
	v_mfma_f32_16x16x32_bf16 v[76:79], v[132:135], v[240:243], v[76:79]
	v_mfma_f32_16x16x32_bf16 v[72:75], v[140:143], v[240:243], v[72:75]
	v_mfma_f32_16x16x32_bf16 v[68:71], v[132:135], v[248:251], v[68:71]
	v_mfma_f32_16x16x32_bf16 v[64:67], v[140:143], v[248:251], v[64:67]
	s_setprio 0
	s_setprio 1
	v_mfma_f32_16x16x32_bf16 v[28:31], v[144:147], v[220:223], v[28:31]
	v_mfma_f32_16x16x32_bf16 v[24:27], v[184:187], v[220:223], v[24:27]
	v_mfma_f32_16x16x32_bf16 v[20:23], v[144:147], v[228:231], v[20:23]
	v_mfma_f32_16x16x32_bf16 v[16:19], v[184:187], v[228:231], v[16:19]
	v_mfma_f32_16x16x32_bf16 v[12:15], v[144:147], v[236:239], v[12:15]
	v_mfma_f32_16x16x32_bf16 v[8:11], v[184:187], v[236:239], v[8:11]
	v_mfma_f32_16x16x32_bf16 v[4:7], v[144:147], v[244:247], v[4:7]
	v_mfma_f32_16x16x32_bf16 v[0:3], v[184:187], v[244:247], v[0:3]
	v_mfma_f32_16x16x32_bf16 v[28:31], v[148:151], v[224:227], v[28:31]
	v_mfma_f32_16x16x32_bf16 v[24:27], v[188:191], v[224:227], v[24:27]
	v_mfma_f32_16x16x32_bf16 v[20:23], v[148:151], v[232:235], v[20:23]
	v_mfma_f32_16x16x32_bf16 v[16:19], v[188:191], v[232:235], v[16:19]
	v_mfma_f32_16x16x32_bf16 v[12:15], v[148:151], v[240:243], v[12:15]
	v_mfma_f32_16x16x32_bf16 v[8:11], v[188:191], v[240:243], v[8:11]
	v_mfma_f32_16x16x32_bf16 v[4:7], v[148:151], v[248:251], v[4:7]
	v_mfma_f32_16x16x32_bf16 v[0:3], v[188:191], v[248:251], v[0:3]
	s_setprio 0
	s_barrier
	s_add_i32 s49, s49, 2
	s_add_u32 s60, s60, 0x100
	s_addc_u32 s61, s61, 0
	s_add_u32 s43, s43, 0x100
	s_addc_u32 s48, s48, 0
	s_cmp_gt_u32 s49, 13
	s_cbranch_scc0 .LBB0_186
	s_and_b64 vcc, exec, s[18:19]
	s_cbranch_vccnz .LBB0_190
	s_lshl_b32 s4, s10, 8
	s_cmp_lt_i32 s58, 8
	s_mov_b64 s[10:11], -1
	s_cbranch_scc0 .LBB0_191

.LBB0_703:
	s_add_u32 s58, s22, 0x100
	v_mov_b32_e32 v0, 0
	s_addc_u32 s59, s23, 0
	s_mov_b32 s60, -2
	v_mov_b32_e32 v1, v0
	v_mov_b32_e32 v2, v0
	v_mov_b32_e32 v3, v0
	v_mov_b32_e32 v4, v0
	v_mov_b32_e32 v5, v0
	v_mov_b32_e32 v6, v0
	v_mov_b32_e32 v7, v0
	v_mov_b32_e32 v12, v0
	v_mov_b32_e32 v13, v0
	v_mov_b32_e32 v14, v0
	v_mov_b32_e32 v15, v0
	v_mov_b32_e32 v20, v0
	v_mov_b32_e32 v21, v0
	v_mov_b32_e32 v22, v0
	v_mov_b32_e32 v23, v0
	v_mov_b32_e32 v28, v0
	v_mov_b32_e32 v29, v0
	v_mov_b32_e32 v30, v0
	v_mov_b32_e32 v31, v0
	v_mov_b32_e32 v36, v0
	v_mov_b32_e32 v37, v0
	v_mov_b32_e32 v38, v0
	v_mov_b32_e32 v39, v0
	v_mov_b32_e32 v44, v0
	v_mov_b32_e32 v45, v0
	v_mov_b32_e32 v46, v0
	v_mov_b32_e32 v47, v0
	v_mov_b32_e32 v52, v0
	v_mov_b32_e32 v53, v0
	v_mov_b32_e32 v54, v0
	v_mov_b32_e32 v55, v0
	v_mov_b32_e32 v8, v0
	v_mov_b32_e32 v9, v0
	v_mov_b32_e32 v10, v0
	v_mov_b32_e32 v11, v0
	v_mov_b32_e32 v16, v0
	v_mov_b32_e32 v17, v0
	v_mov_b32_e32 v18, v0
	v_mov_b32_e32 v19, v0
	v_mov_b32_e32 v24, v0
	v_mov_b32_e32 v25, v0
	v_mov_b32_e32 v26, v0
	v_mov_b32_e32 v27, v0
	v_mov_b32_e32 v32, v0
	v_mov_b32_e32 v33, v0
	v_mov_b32_e32 v34, v0
	v_mov_b32_e32 v35, v0
	v_mov_b32_e32 v40, v0
	v_mov_b32_e32 v41, v0
	v_mov_b32_e32 v42, v0
	v_mov_b32_e32 v43, v0
	v_mov_b32_e32 v48, v0
	v_mov_b32_e32 v49, v0
	v_mov_b32_e32 v50, v0
	v_mov_b32_e32 v51, v0
	v_mov_b32_e32 v56, v0
	v_mov_b32_e32 v57, v0
	v_mov_b32_e32 v58, v0
	v_mov_b32_e32 v59, v0
	v_mov_b32_e32 v60, v0
	v_mov_b32_e32 v61, v0
	v_mov_b32_e32 v62, v0
	v_mov_b32_e32 v63, v0
	v_mov_b32_e32 v64, v0
	v_mov_b32_e32 v65, v0
	v_mov_b32_e32 v66, v0
	v_mov_b32_e32 v67, v0
	v_mov_b32_e32 v68, v0
	v_mov_b32_e32 v69, v0
	v_mov_b32_e32 v70, v0
	v_mov_b32_e32 v71, v0
	v_mov_b32_e32 v76, v0
	v_mov_b32_e32 v77, v0
	v_mov_b32_e32 v78, v0
	v_mov_b32_e32 v79, v0
	v_mov_b32_e32 v84, v0
	v_mov_b32_e32 v85, v0
	v_mov_b32_e32 v86, v0
	v_mov_b32_e32 v87, v0
	v_mov_b32_e32 v92, v0
	v_mov_b32_e32 v93, v0
	v_mov_b32_e32 v94, v0
	v_mov_b32_e32 v95, v0
	v_mov_b32_e32 v100, v0
	v_mov_b32_e32 v101, v0
	v_mov_b32_e32 v102, v0
	v_mov_b32_e32 v103, v0
	v_mov_b32_e32 v108, v0
	v_mov_b32_e32 v109, v0
	v_mov_b32_e32 v110, v0
	v_mov_b32_e32 v111, v0
	v_mov_b32_e32 v116, v0
	v_mov_b32_e32 v117, v0
	v_mov_b32_e32 v118, v0
	v_mov_b32_e32 v119, v0
	v_mov_b32_e32 v72, v0
	v_mov_b32_e32 v73, v0
	v_mov_b32_e32 v74, v0
	v_mov_b32_e32 v75, v0
	v_mov_b32_e32 v80, v0
	v_mov_b32_e32 v81, v0
	v_mov_b32_e32 v82, v0
	v_mov_b32_e32 v83, v0
	v_mov_b32_e32 v88, v0
	v_mov_b32_e32 v89, v0
	v_mov_b32_e32 v90, v0
	v_mov_b32_e32 v91, v0
	v_mov_b32_e32 v96, v0
	v_mov_b32_e32 v97, v0
	v_mov_b32_e32 v98, v0
	v_mov_b32_e32 v99, v0
	v_mov_b32_e32 v104, v0
	v_mov_b32_e32 v105, v0
	v_mov_b32_e32 v106, v0
	v_mov_b32_e32 v107, v0
	v_mov_b32_e32 v112, v0
	v_mov_b32_e32 v113, v0
	v_mov_b32_e32 v114, v0
	v_mov_b32_e32 v115, v0
	v_mov_b32_e32 v120, v0
	v_mov_b32_e32 v121, v0
	v_mov_b32_e32 v122, v0
	v_mov_b32_e32 v123, v0
	v_mov_b32_e32 v124, v0
	v_mov_b32_e32 v125, v0
	v_mov_b32_e32 v126, v0
	v_mov_b32_e32 v127, v0
	s_nop 0
	s_nop 0
	s_nop 0
	s_nop 0
	s_nop 0
	s_nop 0
	s_nop 0
	s_nop 0
	s_nop 0
	s_nop 0
	s_nop 0
	s_nop 0

.LBB0_723:
	s_ashr_i32 s27, s26, 31
	s_lshl_b64 s[28:29], s[26:27], 17
	s_add_u32 s28, s50, s28
	s_addc_u32 s29, s51, s29
	s_and_b64 s[30:31], s[6:7], exec
	s_cselect_b32 s27, s29, s53
	s_cselect_b32 s79, s28, s52
	s_ashr_i32 s25, s24, 31
	s_lshl_b64 s[30:31], s[24:25], 17
	s_add_u32 s30, s48, s30
	s_addc_u32 s31, s49, s31
	s_and_b64 s[46:47], s[6:7], exec
	v_mov_b32_e32 v0, 0
	s_cselect_b32 s25, s31, s43
	s_cselect_b32 s80, s30, s42
	s_mov_b32 s46, 0
	s_mov_b64 s[54:55], -1
	s_mov_b64 s[56:57], 0
	v_mov_b32_e32 v1, v0
	v_mov_b32_e32 v2, v0
	v_mov_b32_e32 v3, v0
	v_mov_b32_e32 v4, v0
	v_mov_b32_e32 v5, v0
	v_mov_b32_e32 v6, v0
	v_mov_b32_e32 v7, v0
	v_mov_b32_e32 v12, v0
	v_mov_b32_e32 v13, v0
	v_mov_b32_e32 v14, v0
	v_mov_b32_e32 v15, v0
	v_mov_b32_e32 v20, v0
	v_mov_b32_e32 v21, v0
	v_mov_b32_e32 v22, v0
	v_mov_b32_e32 v23, v0
	v_mov_b32_e32 v28, v0
	v_mov_b32_e32 v29, v0
	v_mov_b32_e32 v30, v0
	v_mov_b32_e32 v31, v0
	v_mov_b32_e32 v36, v0
	v_mov_b32_e32 v37, v0
	v_mov_b32_e32 v38, v0
	v_mov_b32_e32 v39, v0
	v_mov_b32_e32 v44, v0
	v_mov_b32_e32 v45, v0
	v_mov_b32_e32 v46, v0
	v_mov_b32_e32 v47, v0
	v_mov_b32_e32 v52, v0
	v_mov_b32_e32 v53, v0
	v_mov_b32_e32 v54, v0
	v_mov_b32_e32 v55, v0
	v_mov_b32_e32 v8, v0
	v_mov_b32_e32 v9, v0
	v_mov_b32_e32 v10, v0
	v_mov_b32_e32 v11, v0
	v_mov_b32_e32 v16, v0
	v_mov_b32_e32 v17, v0
	v_mov_b32_e32 v18, v0
	v_mov_b32_e32 v19, v0
	v_mov_b32_e32 v24, v0
	v_mov_b32_e32 v25, v0
	v_mov_b32_e32 v26, v0
	v_mov_b32_e32 v27, v0
	v_mov_b32_e32 v32, v0
	v_mov_b32_e32 v33, v0
	v_mov_b32_e32 v34, v0
	v_mov_b32_e32 v35, v0
	v_mov_b32_e32 v40, v0
	v_mov_b32_e32 v41, v0
	v_mov_b32_e32 v42, v0
	v_mov_b32_e32 v43, v0
	v_mov_b32_e32 v48, v0
	v_mov_b32_e32 v49, v0
	v_mov_b32_e32 v50, v0
	v_mov_b32_e32 v51, v0
	v_mov_b32_e32 v56, v0
	v_mov_b32_e32 v57, v0
	v_mov_b32_e32 v58, v0
	v_mov_b32_e32 v59, v0
	v_mov_b32_e32 v60, v0
	v_mov_b32_e32 v61, v0
	v_mov_b32_e32 v62, v0
	v_mov_b32_e32 v63, v0
	v_mov_b32_e32 v64, v0
	v_mov_b32_e32 v65, v0
	v_mov_b32_e32 v66, v0
	v_mov_b32_e32 v67, v0
	v_mov_b32_e32 v68, v0
	v_mov_b32_e32 v69, v0
	v_mov_b32_e32 v70, v0
	v_mov_b32_e32 v71, v0
	v_mov_b32_e32 v76, v0
	v_mov_b32_e32 v77, v0
	v_mov_b32_e32 v78, v0
	v_mov_b32_e32 v79, v0
	v_mov_b32_e32 v84, v0
	v_mov_b32_e32 v85, v0
	v_mov_b32_e32 v86, v0
	v_mov_b32_e32 v87, v0
	v_mov_b32_e32 v92, v0
	v_mov_b32_e32 v93, v0
	v_mov_b32_e32 v94, v0
	v_mov_b32_e32 v95, v0
	v_mov_b32_e32 v100, v0
	v_mov_b32_e32 v101, v0
	v_mov_b32_e32 v102, v0
	v_mov_b32_e32 v103, v0
	v_mov_b32_e32 v108, v0
	v_mov_b32_e32 v109, v0
	v_mov_b32_e32 v110, v0
	v_mov_b32_e32 v111, v0
	v_mov_b32_e32 v116, v0
	v_mov_b32_e32 v117, v0
	v_mov_b32_e32 v118, v0
	v_mov_b32_e32 v119, v0
	v_mov_b32_e32 v72, v0
	v_mov_b32_e32 v73, v0
	v_mov_b32_e32 v74, v0
	v_mov_b32_e32 v75, v0
	v_mov_b32_e32 v80, v0
	v_mov_b32_e32 v81, v0
	v_mov_b32_e32 v82, v0
	v_mov_b32_e32 v83, v0
	v_mov_b32_e32 v88, v0
	v_mov_b32_e32 v89, v0
	v_mov_b32_e32 v90, v0
	v_mov_b32_e32 v91, v0
	v_mov_b32_e32 v96, v0
	v_mov_b32_e32 v97, v0
	v_mov_b32_e32 v98, v0
	v_mov_b32_e32 v99, v0
	v_mov_b32_e32 v104, v0
	v_mov_b32_e32 v105, v0
	v_mov_b32_e32 v106, v0
	v_mov_b32_e32 v107, v0
	v_mov_b32_e32 v112, v0
	v_mov_b32_e32 v113, v0
	v_mov_b32_e32 v114, v0
	v_mov_b32_e32 v115, v0
	v_mov_b32_e32 v120, v0
	v_mov_b32_e32 v121, v0
	v_mov_b32_e32 v122, v0
	v_mov_b32_e32 v123, v0
	v_mov_b32_e32 v124, v0
	v_mov_b32_e32 v125, v0
	v_mov_b32_e32 v126, v0
	v_mov_b32_e32 v127, v0
	s_nop 0
	s_nop 0
	s_nop 0
	s_nop 0

.LBB0_1076:
	s_ashr_i32 s29, s28, 31
	s_lshl_b64 s[30:31], s[28:29], 19
	s_add_u32 s30, s3, s30
	s_addc_u32 s31, s45, s31
	s_and_b64 s[40:41], s[6:7], exec
	s_cselect_b32 s29, s31, s53
	s_cselect_b32 s65, s30, s52
	s_ashr_i32 s27, s26, 31
	s_lshl_b64 s[40:41], s[26:27], 19
	s_add_u32 s40, s62, s40
	s_addc_u32 s41, s63, s41
	s_and_b64 s[46:47], s[6:7], exec
	s_cselect_b32 s27, s41, s55
	s_cselect_b32 s66, s40, s54
	s_add_u32 s52, s52, 0x40080
	s_addc_u32 s53, s53, 0
	s_add_u32 s67, s54, 0x100
	v_mov_b32_e32 v0, 0
	s_addc_u32 s68, s55, 0
	s_mov_b32 s69, -2
	v_mov_b32_e32 v1, v0
	v_mov_b32_e32 v2, v0
	v_mov_b32_e32 v3, v0
	v_mov_b32_e32 v4, v0
	v_mov_b32_e32 v5, v0
	v_mov_b32_e32 v6, v0
	v_mov_b32_e32 v7, v0
	v_mov_b32_e32 v16, v0
	v_mov_b32_e32 v17, v0
	v_mov_b32_e32 v18, v0
	v_mov_b32_e32 v19, v0
	v_mov_b32_e32 v20, v0
	v_mov_b32_e32 v21, v0
	v_mov_b32_e32 v22, v0
	v_mov_b32_e32 v23, v0
	v_mov_b32_e32 v32, v0
	v_mov_b32_e32 v33, v0
	v_mov_b32_e32 v34, v0
	v_mov_b32_e32 v35, v0
	v_mov_b32_e32 v36, v0
	v_mov_b32_e32 v37, v0
	v_mov_b32_e32 v38, v0
	v_mov_b32_e32 v39, v0
	v_mov_b32_e32 v48, v0
	v_mov_b32_e32 v49, v0
	v_mov_b32_e32 v50, v0
	v_mov_b32_e32 v51, v0
	v_mov_b32_e32 v52, v0
	v_mov_b32_e32 v53, v0
	v_mov_b32_e32 v54, v0
	v_mov_b32_e32 v55, v0
	v_mov_b32_e32 v8, v0
	v_mov_b32_e32 v9, v0
	v_mov_b32_e32 v10, v0
	v_mov_b32_e32 v11, v0
	v_mov_b32_e32 v12, v0
	v_mov_b32_e32 v13, v0
	v_mov_b32_e32 v14, v0
	v_mov_b32_e32 v15, v0
	v_mov_b32_e32 v24, v0
	v_mov_b32_e32 v25, v0
	v_mov_b32_e32 v26, v0
	v_mov_b32_e32 v27, v0
	v_mov_b32_e32 v28, v0
	v_mov_b32_e32 v29, v0
	v_mov_b32_e32 v30, v0
	v_mov_b32_e32 v31, v0
	v_mov_b32_e32 v40, v0
	v_mov_b32_e32 v41, v0
	v_mov_b32_e32 v42, v0
	v_mov_b32_e32 v43, v0
	v_mov_b32_e32 v44, v0
	v_mov_b32_e32 v45, v0
	v_mov_b32_e32 v46, v0
	v_mov_b32_e32 v47, v0
	v_mov_b32_e32 v56, v0
	v_mov_b32_e32 v57, v0
	v_mov_b32_e32 v58, v0
	v_mov_b32_e32 v59, v0
	v_mov_b32_e32 v60, v0
	v_mov_b32_e32 v61, v0
	v_mov_b32_e32 v62, v0
	v_mov_b32_e32 v63, v0
	v_mov_b32_e32 v64, v0
	v_mov_b32_e32 v65, v0
	v_mov_b32_e32 v66, v0
	v_mov_b32_e32 v67, v0
	v_mov_b32_e32 v68, v0
	v_mov_b32_e32 v69, v0
	v_mov_b32_e32 v70, v0
	v_mov_b32_e32 v71, v0
	v_mov_b32_e32 v80, v0
	v_mov_b32_e32 v81, v0
	v_mov_b32_e32 v82, v0
	v_mov_b32_e32 v83, v0
	v_mov_b32_e32 v84, v0
	v_mov_b32_e32 v85, v0
	v_mov_b32_e32 v86, v0
	v_mov_b32_e32 v87, v0
	v_mov_b32_e32 v96, v0
	v_mov_b32_e32 v97, v0
	v_mov_b32_e32 v98, v0
	v_mov_b32_e32 v99, v0
	v_mov_b32_e32 v100, v0
	v_mov_b32_e32 v101, v0
	v_mov_b32_e32 v102, v0
	v_mov_b32_e32 v103, v0
	v_mov_b32_e32 v112, v0
	v_mov_b32_e32 v113, v0
	v_mov_b32_e32 v114, v0
	v_mov_b32_e32 v115, v0
	v_mov_b32_e32 v116, v0
	v_mov_b32_e32 v117, v0
	v_mov_b32_e32 v118, v0
	v_mov_b32_e32 v119, v0
	v_mov_b32_e32 v72, v0
	v_mov_b32_e32 v73, v0
	v_mov_b32_e32 v74, v0
	v_mov_b32_e32 v75, v0
	v_mov_b32_e32 v76, v0
	v_mov_b32_e32 v77, v0
	v_mov_b32_e32 v78, v0
	v_mov_b32_e32 v79, v0
	v_mov_b32_e32 v88, v0
	v_mov_b32_e32 v89, v0
	v_mov_b32_e32 v90, v0
	v_mov_b32_e32 v91, v0
	v_mov_b32_e32 v92, v0
	v_mov_b32_e32 v93, v0
	v_mov_b32_e32 v94, v0
	v_mov_b32_e32 v95, v0
	v_mov_b32_e32 v104, v0
	v_mov_b32_e32 v105, v0
	v_mov_b32_e32 v106, v0
	v_mov_b32_e32 v107, v0
	v_mov_b32_e32 v108, v0
	v_mov_b32_e32 v109, v0
	v_mov_b32_e32 v110, v0
	v_mov_b32_e32 v111, v0
	v_mov_b32_e32 v120, v0
	v_mov_b32_e32 v121, v0
	v_mov_b32_e32 v122, v0
	v_mov_b32_e32 v123, v0
	v_mov_b32_e32 v124, v0
	v_mov_b32_e32 v125, v0
	v_mov_b32_e32 v126, v0
	v_mov_b32_e32 v127, v0
	s_nop 0
	s_nop 0
	s_nop 0
	s_nop 0
	s_nop 0
	s_nop 0
	s_nop 0
	s_nop 0
	s_nop 0
	s_nop 0
	s_nop 0
	s_nop 0
	s_nop 0
	s_nop 0

.LBB0_1305:
	s_ashr_i32 s57, s56, 31
	s_lshl_b64 s[46:47], s[56:57], 19
	s_add_u32 s58, s3, s46
	s_addc_u32 s59, s45, s47
	s_and_b64 s[46:47], s[60:61], exec
	s_cselect_b32 s35, s59, s69
	s_cselect_b32 s57, s58, s68
	s_ashr_i32 s55, s54, 31
	s_lshl_b64 s[46:47], s[54:55], 19
	s_add_u32 s62, s75, s46
	s_addc_u32 s63, s76, s47
	s_and_b64 s[46:47], s[60:61], exec
	s_cselect_b32 s55, s63, s71
	s_cselect_b32 s65, s62, s70
	s_add_u32 s68, s68, 0x40080
	s_addc_u32 s69, s69, 0
	s_add_u32 s67, s70, 0x100
	v_mov_b32_e32 v0, 0
	s_addc_u32 s83, s71, 0
	s_mov_b32 s84, -2
	v_mov_b32_e32 v1, v0
	v_mov_b32_e32 v2, v0
	v_mov_b32_e32 v3, v0
	v_mov_b32_e32 v8, v0
	v_mov_b32_e32 v9, v0
	v_mov_b32_e32 v10, v0
	v_mov_b32_e32 v11, v0
	s_waitcnt vmcnt(0)
	v_mov_b32_e32 v24, v0
	v_mov_b32_e32 v25, v0
	v_mov_b32_e32 v26, v0
	v_mov_b32_e32 v27, v0
	v_mov_b32_e32 v28, v0
	v_mov_b32_e32 v29, v0
	v_mov_b32_e32 v30, v0
	v_mov_b32_e32 v31, v0
	v_mov_b32_e32 v40, v0
	v_mov_b32_e32 v41, v0
	v_mov_b32_e32 v42, v0
	v_mov_b32_e32 v43, v0
	v_mov_b32_e32 v44, v0
	v_mov_b32_e32 v45, v0
	v_mov_b32_e32 v46, v0
	v_mov_b32_e32 v47, v0
	v_mov_b32_e32 v72, v0
	v_mov_b32_e32 v73, v0
	v_mov_b32_e32 v74, v0
	v_mov_b32_e32 v75, v0
	v_mov_b32_e32 v92, v0
	v_mov_b32_e32 v93, v0
	v_mov_b32_e32 v94, v0
	v_mov_b32_e32 v95, v0
	v_mov_b32_e32 v4, v0
	v_mov_b32_e32 v5, v0
	v_mov_b32_e32 v6, v0
	v_mov_b32_e32 v7, v0
	v_mov_b32_e32 v16, v0
	v_mov_b32_e32 v17, v0
	v_mov_b32_e32 v18, v0
	v_mov_b32_e32 v19, v0
	v_mov_b32_e32 v12, v0
	v_mov_b32_e32 v13, v0
	v_mov_b32_e32 v14, v0
	v_mov_b32_e32 v15, v0
	v_mov_b32_e32 v20, v0
	v_mov_b32_e32 v21, v0
	v_mov_b32_e32 v22, v0
	v_mov_b32_e32 v23, v0
	v_mov_b32_e32 v32, v0
	v_mov_b32_e32 v33, v0
	v_mov_b32_e32 v34, v0
	v_mov_b32_e32 v35, v0
	v_mov_b32_e32 v36, v0
	v_mov_b32_e32 v37, v0
	v_mov_b32_e32 v38, v0
	v_mov_b32_e32 v39, v0
	v_mov_b32_e32 v48, v0
	v_mov_b32_e32 v49, v0
	v_mov_b32_e32 v50, v0
	v_mov_b32_e32 v51, v0
	v_mov_b32_e32 v68, v0
	v_mov_b32_e32 v69, v0
	v_mov_b32_e32 v70, v0
	v_mov_b32_e32 v71, v0
	v_mov_b32_e32 v96, v0
	v_mov_b32_e32 v97, v0
	v_mov_b32_e32 v98, v0
	v_mov_b32_e32 v99, v0
	v_mov_b32_e32 v104, v0
	v_mov_b32_e32 v105, v0
	v_mov_b32_e32 v106, v0
	v_mov_b32_e32 v107, v0
	v_mov_b32_e32 v120, v0
	v_mov_b32_e32 v121, v0
	v_mov_b32_e32 v122, v0
	v_mov_b32_e32 v123, v0
	v_mov_b32_e32 v124, v0
	v_mov_b32_e32 v125, v0
	v_mov_b32_e32 v126, v0
	v_mov_b32_e32 v127, v0
	v_mov_b32_e32 v136, v0
	v_mov_b32_e32 v137, v0
	v_mov_b32_e32 v138, v0
	v_mov_b32_e32 v139, v0
	v_mov_b32_e32 v140, v0
	v_mov_b32_e32 v141, v0
	v_mov_b32_e32 v142, v0
	v_mov_b32_e32 v143, v0
	v_mov_b32_e32 v152, v0
	v_mov_b32_e32 v153, v0
	v_mov_b32_e32 v154, v0
	v_mov_b32_e32 v155, v0
	v_mov_b32_e32 v156, v0
	v_mov_b32_e32 v157, v0
	v_mov_b32_e32 v158, v0
	v_mov_b32_e32 v159, v0
	v_mov_b32_e32 v100, v0
	v_mov_b32_e32 v101, v0
	v_mov_b32_e32 v102, v0
	v_mov_b32_e32 v103, v0
	v_mov_b32_e32 v112, v0
	v_mov_b32_e32 v113, v0
	v_mov_b32_e32 v114, v0
	v_mov_b32_e32 v115, v0
	v_mov_b32_e32 v108, v0
	v_mov_b32_e32 v109, v0
	v_mov_b32_e32 v110, v0
	v_mov_b32_e32 v111, v0
	v_mov_b32_e32 v116, v0
	v_mov_b32_e32 v117, v0
	v_mov_b32_e32 v118, v0
	v_mov_b32_e32 v119, v0
	v_mov_b32_e32 v128, v0
	v_mov_b32_e32 v129, v0
	v_mov_b32_e32 v130, v0
	v_mov_b32_e32 v131, v0
	v_mov_b32_e32 v132, v0
	v_mov_b32_e32 v133, v0
	v_mov_b32_e32 v134, v0
	v_mov_b32_e32 v135, v0
	v_mov_b32_e32 v144, v0
	v_mov_b32_e32 v145, v0
	v_mov_b32_e32 v146, v0
	v_mov_b32_e32 v147, v0
	v_mov_b32_e32 v148, v0
	v_mov_b32_e32 v149, v0
	v_mov_b32_e32 v150, v0
	v_mov_b32_e32 v151, v0
	s_nop 0
	s_nop 0
	s_nop 0
	s_nop 0
	s_nop 0
	s_nop 0
	s_nop 0
	s_nop 0
	s_nop 0
	s_nop 0
	s_nop 0
	s_nop 0
	s_nop 0
	s_nop 0

.LBB0_1482:
	s_ashr_i32 s59, s58, 31
	s_lshl_b64 s[46:47], s[58:59], 19
	s_add_u32 s60, s3, s46
	s_addc_u32 s61, s4, s47
	s_and_b64 s[46:47], s[8:9], exec
	s_cselect_b32 s11, s61, s67
	s_cselect_b32 s35, s60, s66
	s_ashr_i32 s57, s56, 31
	s_lshl_b64 s[46:47], s[56:57], 19
	s_add_u32 s62, s5, s46
	s_addc_u32 s63, s45, s47
	s_and_b64 s[46:47], s[8:9], exec
	s_cselect_b32 s57, s63, s69
	s_cselect_b32 s59, s62, s68
	s_add_u32 s66, s66, 0x40080
	s_addc_u32 s67, s67, 0
	s_add_u32 s65, s68, 0x100
	v_mov_b32_e32 v0, 0
	s_addc_u32 s83, s69, 0
	s_mov_b32 s84, -2
	v_mov_b32_e32 v1, v0
	v_mov_b32_e32 v2, v0
	v_mov_b32_e32 v3, v0
	v_mov_b32_e32 v8, v0
	v_mov_b32_e32 v9, v0
	v_mov_b32_e32 v10, v0
	v_mov_b32_e32 v11, v0
	v_mov_b32_e32 v24, v0
	v_mov_b32_e32 v25, v0
	v_mov_b32_e32 v26, v0
	v_mov_b32_e32 v27, v0
	v_mov_b32_e32 v28, v0
	v_mov_b32_e32 v29, v0
	v_mov_b32_e32 v30, v0
	v_mov_b32_e32 v31, v0
	v_mov_b32_e32 v40, v0
	v_mov_b32_e32 v41, v0
	v_mov_b32_e32 v42, v0
	v_mov_b32_e32 v43, v0
	v_mov_b32_e32 v44, v0
	v_mov_b32_e32 v45, v0
	v_mov_b32_e32 v46, v0
	v_mov_b32_e32 v47, v0
	v_mov_b32_e32 v56, v0
	v_mov_b32_e32 v57, v0
	v_mov_b32_e32 v58, v0
	v_mov_b32_e32 v59, v0
	v_mov_b32_e32 v60, v0
	v_mov_b32_e32 v61, v0
	v_mov_b32_e32 v62, v0
	v_mov_b32_e32 v63, v0
	v_mov_b32_e32 v4, v0
	v_mov_b32_e32 v5, v0
	v_mov_b32_e32 v6, v0
	v_mov_b32_e32 v7, v0
	v_mov_b32_e32 v16, v0
	v_mov_b32_e32 v17, v0
	v_mov_b32_e32 v18, v0
	v_mov_b32_e32 v19, v0
	v_mov_b32_e32 v12, v0
	v_mov_b32_e32 v13, v0
	v_mov_b32_e32 v14, v0
	v_mov_b32_e32 v15, v0
	v_mov_b32_e32 v20, v0
	v_mov_b32_e32 v21, v0
	v_mov_b32_e32 v22, v0
	v_mov_b32_e32 v23, v0
	v_mov_b32_e32 v32, v0
	v_mov_b32_e32 v33, v0
	v_mov_b32_e32 v34, v0
	v_mov_b32_e32 v35, v0
	v_mov_b32_e32 v36, v0
	v_mov_b32_e32 v37, v0
	v_mov_b32_e32 v38, v0
	v_mov_b32_e32 v39, v0
	v_mov_b32_e32 v48, v0
	v_mov_b32_e32 v49, v0
	v_mov_b32_e32 v50, v0
	v_mov_b32_e32 v51, v0
	v_mov_b32_e32 v52, v0
	v_mov_b32_e32 v53, v0
	v_mov_b32_e32 v54, v0
	v_mov_b32_e32 v55, v0
	v_mov_b32_e32 v64, v0
	v_mov_b32_e32 v65, v0
	v_mov_b32_e32 v66, v0
	v_mov_b32_e32 v67, v0
	v_mov_b32_e32 v88, v0
	v_mov_b32_e32 v89, v0
	v_mov_b32_e32 v90, v0
	v_mov_b32_e32 v91, v0
	v_mov_b32_e32 v120, v0
	v_mov_b32_e32 v121, v0
	v_mov_b32_e32 v122, v0
	v_mov_b32_e32 v123, v0
	v_mov_b32_e32 v124, v0
	v_mov_b32_e32 v125, v0
	v_mov_b32_e32 v126, v0
	v_mov_b32_e32 v127, v0
	v_mov_b32_e32 v136, v0
	v_mov_b32_e32 v137, v0
	v_mov_b32_e32 v138, v0
	v_mov_b32_e32 v139, v0
	v_mov_b32_e32 v140, v0
	v_mov_b32_e32 v141, v0
	v_mov_b32_e32 v142, v0
	v_mov_b32_e32 v143, v0
	v_mov_b32_e32 v152, v0
	v_mov_b32_e32 v153, v0
	v_mov_b32_e32 v154, v0
	v_mov_b32_e32 v155, v0
	v_mov_b32_e32 v158, v0
	v_mov_b32_e32 v159, v0
	v_mov_b32_e32 v160, v0
	v_mov_b32_e32 v161, v0
	v_mov_b32_e32 v80, v0
	v_mov_b32_e32 v81, v0
	v_mov_b32_e32 v82, v0
	v_mov_b32_e32 v83, v0
	v_mov_b32_e32 v112, v0
	v_mov_b32_e32 v113, v0
	v_mov_b32_e32 v114, v0
	v_mov_b32_e32 v115, v0
	v_mov_b32_e32 v92, v0
	v_mov_b32_e32 v93, v0
	v_mov_b32_e32 v94, v0
	v_mov_b32_e32 v95, v0
	v_mov_b32_e32 v116, v0
	v_mov_b32_e32 v117, v0
	v_mov_b32_e32 v118, v0
	v_mov_b32_e32 v119, v0
	v_mov_b32_e32 v128, v0
	v_mov_b32_e32 v129, v0
	v_mov_b32_e32 v130, v0
	v_mov_b32_e32 v131, v0
	v_mov_b32_e32 v132, v0
	v_mov_b32_e32 v133, v0
	v_mov_b32_e32 v134, v0
	v_mov_b32_e32 v135, v0
	v_mov_b32_e32 v144, v0
	v_mov_b32_e32 v145, v0
	v_mov_b32_e32 v146, v0
	v_mov_b32_e32 v147, v0
	v_mov_b32_e32 v148, v0
	v_mov_b32_e32 v149, v0
	v_mov_b32_e32 v150, v0
	v_mov_b32_e32 v151, v0
	s_nop 0
	s_nop 0
	s_nop 0
	s_nop 0
	s_nop 0
	s_nop 0
	s_nop 0
	s_nop 0

.LBB0_1583:
	s_add_u32 s65, s40, 0x100
	v_mov_b32_e32 v0, 0
	s_addc_u32 s66, s41, 0
	s_mov_b32 s67, -2
	v_mov_b32_e32 v1, v0
	v_mov_b32_e32 v2, v0
	v_mov_b32_e32 v3, v0
	v_mov_b32_e32 v4, v0
	v_mov_b32_e32 v5, v0
	v_mov_b32_e32 v6, v0
	v_mov_b32_e32 v7, v0
	v_mov_b32_e32 v16, v0
	v_mov_b32_e32 v17, v0
	v_mov_b32_e32 v18, v0
	v_mov_b32_e32 v19, v0
	v_mov_b32_e32 v20, v0
	v_mov_b32_e32 v21, v0
	v_mov_b32_e32 v22, v0
	v_mov_b32_e32 v23, v0
	v_mov_b32_e32 v32, v0
	v_mov_b32_e32 v33, v0
	v_mov_b32_e32 v34, v0
	v_mov_b32_e32 v35, v0
	v_mov_b32_e32 v36, v0
	v_mov_b32_e32 v37, v0
	v_mov_b32_e32 v38, v0
	v_mov_b32_e32 v39, v0
	v_mov_b32_e32 v48, v0
	v_mov_b32_e32 v49, v0
	v_mov_b32_e32 v50, v0
	v_mov_b32_e32 v51, v0
	v_mov_b32_e32 v52, v0
	v_mov_b32_e32 v53, v0
	v_mov_b32_e32 v54, v0
	v_mov_b32_e32 v55, v0
	v_mov_b32_e32 v8, v0
	v_mov_b32_e32 v9, v0
	v_mov_b32_e32 v10, v0
	v_mov_b32_e32 v11, v0
	v_mov_b32_e32 v12, v0
	v_mov_b32_e32 v13, v0
	v_mov_b32_e32 v14, v0
	v_mov_b32_e32 v15, v0
	v_mov_b32_e32 v24, v0
	v_mov_b32_e32 v25, v0
	v_mov_b32_e32 v26, v0
	v_mov_b32_e32 v27, v0
	v_mov_b32_e32 v28, v0
	v_mov_b32_e32 v29, v0
	v_mov_b32_e32 v30, v0
	v_mov_b32_e32 v31, v0
	v_mov_b32_e32 v40, v0
	v_mov_b32_e32 v41, v0
	v_mov_b32_e32 v42, v0
	v_mov_b32_e32 v43, v0
	v_mov_b32_e32 v44, v0
	v_mov_b32_e32 v45, v0
	v_mov_b32_e32 v46, v0
	v_mov_b32_e32 v47, v0
	v_mov_b32_e32 v56, v0
	v_mov_b32_e32 v57, v0
	v_mov_b32_e32 v58, v0
	v_mov_b32_e32 v59, v0
	v_mov_b32_e32 v60, v0
	v_mov_b32_e32 v61, v0
	v_mov_b32_e32 v62, v0
	v_mov_b32_e32 v63, v0
	v_mov_b32_e32 v64, v0
	v_mov_b32_e32 v65, v0
	v_mov_b32_e32 v66, v0
	v_mov_b32_e32 v67, v0
	v_mov_b32_e32 v68, v0
	v_mov_b32_e32 v69, v0
	v_mov_b32_e32 v70, v0
	v_mov_b32_e32 v71, v0
	v_mov_b32_e32 v80, v0
	v_mov_b32_e32 v81, v0
	v_mov_b32_e32 v82, v0
	v_mov_b32_e32 v83, v0
	v_mov_b32_e32 v84, v0
	v_mov_b32_e32 v85, v0
	v_mov_b32_e32 v86, v0
	v_mov_b32_e32 v87, v0
	v_mov_b32_e32 v96, v0
	v_mov_b32_e32 v97, v0
	v_mov_b32_e32 v98, v0
	v_mov_b32_e32 v99, v0
	v_mov_b32_e32 v100, v0
	v_mov_b32_e32 v101, v0
	v_mov_b32_e32 v102, v0
	v_mov_b32_e32 v103, v0
	v_mov_b32_e32 v112, v0
	v_mov_b32_e32 v113, v0
	v_mov_b32_e32 v114, v0
	v_mov_b32_e32 v115, v0
	v_mov_b32_e32 v116, v0
	v_mov_b32_e32 v117, v0
	v_mov_b32_e32 v118, v0
	v_mov_b32_e32 v119, v0
	v_mov_b32_e32 v72, v0
	v_mov_b32_e32 v73, v0
	v_mov_b32_e32 v74, v0
	v_mov_b32_e32 v75, v0
	v_mov_b32_e32 v76, v0
	v_mov_b32_e32 v77, v0
	v_mov_b32_e32 v78, v0
	v_mov_b32_e32 v79, v0
	v_mov_b32_e32 v88, v0
	v_mov_b32_e32 v89, v0
	v_mov_b32_e32 v90, v0
	v_mov_b32_e32 v91, v0
	v_mov_b32_e32 v92, v0
	v_mov_b32_e32 v93, v0
	v_mov_b32_e32 v94, v0
	v_mov_b32_e32 v95, v0
	v_mov_b32_e32 v104, v0
	v_mov_b32_e32 v105, v0
	v_mov_b32_e32 v106, v0
	v_mov_b32_e32 v107, v0
	v_mov_b32_e32 v108, v0
	v_mov_b32_e32 v109, v0
	v_mov_b32_e32 v110, v0
	v_mov_b32_e32 v111, v0
	v_mov_b32_e32 v120, v0
	v_mov_b32_e32 v121, v0
	v_mov_b32_e32 v122, v0
	v_mov_b32_e32 v123, v0
	v_mov_b32_e32 v124, v0
	v_mov_b32_e32 v125, v0
	v_mov_b32_e32 v126, v0
	v_mov_b32_e32 v127, v0
	s_nop 0
	s_nop 0
	s_nop 0
	s_nop 0
	s_nop 0
	s_nop 0
	s_nop 0
.LBB0_1584:
	ds_read_b128 v[144:147], v154
	ds_read_b128 v[158:161], v154 offset:1024
	ds_read_b128 v[162:165], v154 offset:2048
	ds_read_b128 v[166:169], v154 offset:3072
	ds_read_b128 v[170:173], v155
	ds_read_b128 v[174:177], v155 offset:1024
	ds_read_b128 v[178:181], v155 offset:2048
	ds_read_b128 v[182:185], v155 offset:3072
	s_add_u32 s40, s30, 0x100
	s_addc_u32 s41, s31, 0
	s_cmp_eq_u32 s67, 40
	s_cselect_b32 s53, s9, s41
	s_cselect_b32 s52, s8, s40
	s_cselect_b32 s43, s29, s66
	s_cselect_b32 s42, s28, s65
	v_lshl_add_u64 v[148:149], s[30:31], 0, v[136:137]
	s_add_i32 m0, s50, 0xc000
	ds_read_b128 v[186:189], v156
	ds_read_b128 v[190:193], v156 offset:1024
	ds_read_b128 v[198:201], v156 offset:2048
	ds_read_b128 v[202:205], v156 offset:3072
	ds_read_b128 v[206:209], v156 offset:4096
	ds_read_b128 v[210:213], v156 offset:5120
	ds_read_b128 v[214:217], v156 offset:6144
	ds_read_b128 v[218:221], v156 offset:7168
	global_load_lds_dwordx4 v[148:149], off
	v_lshl_add_u64 v[148:149], s[30:31], 0, v[138:139]
	s_add_i32 m0, s50, 0xe000
	s_nop 0
	global_load_lds_dwordx4 v[148:149], off
	s_waitcnt vmcnt(8)
	s_waitcnt lgkmcnt(0)
	s_barrier
	s_setprio 1
	s_waitcnt lgkmcnt(0)
	v_mfma_f32_16x16x32_bf16 v[124:127], v[144:147], v[186:189], v[124:127]
	v_mfma_f32_16x16x32_bf16 v[120:123], v[162:165], v[186:189], v[120:123]
	v_mfma_f32_16x16x32_bf16 v[108:111], v[144:147], v[198:201], v[108:111]
	v_mfma_f32_16x16x32_bf16 v[104:107], v[162:165], v[198:201], v[104:107]
	v_mfma_f32_16x16x32_bf16 v[92:95], v[144:147], v[206:209], v[92:95]
	v_mfma_f32_16x16x32_bf16 v[88:91], v[162:165], v[206:209], v[88:91]
	v_mfma_f32_16x16x32_bf16 v[76:79], v[144:147], v[214:217], v[76:79]
	v_mfma_f32_16x16x32_bf16 v[72:75], v[162:165], v[214:217], v[72:75]
	v_mfma_f32_16x16x32_bf16 v[124:127], v[158:161], v[190:193], v[124:127]
	v_mfma_f32_16x16x32_bf16 v[120:123], v[166:169], v[190:193], v[120:123]
	v_mfma_f32_16x16x32_bf16 v[108:111], v[158:161], v[202:205], v[108:111]
	v_mfma_f32_16x16x32_bf16 v[104:107], v[166:169], v[202:205], v[104:107]
	v_mfma_f32_16x16x32_bf16 v[92:95], v[158:161], v[210:213], v[92:95]
	v_mfma_f32_16x16x32_bf16 v[88:91], v[166:169], v[210:213], v[88:91]
	v_mfma_f32_16x16x32_bf16 v[76:79], v[158:161], v[218:221], v[76:79]
	v_mfma_f32_16x16x32_bf16 v[72:75], v[166:169], v[218:221], v[72:75]
	s_setprio 0
	s_setprio 1
	v_mfma_f32_16x16x32_bf16 v[116:119], v[170:173], v[186:189], v[116:119]
	v_mfma_f32_16x16x32_bf16 v[112:115], v[178:181], v[186:189], v[112:115]
	v_mfma_f32_16x16x32_bf16 v[100:103], v[170:173], v[198:201], v[100:103]
	v_mfma_f32_16x16x32_bf16 v[96:99], v[178:181], v[198:201], v[96:99]
	v_mfma_f32_16x16x32_bf16 v[84:87], v[170:173], v[206:209], v[84:87]
	v_mfma_f32_16x16x32_bf16 v[80:83], v[178:181], v[206:209], v[80:83]
	v_mfma_f32_16x16x32_bf16 v[68:71], v[170:173], v[214:217], v[68:71]
	v_mfma_f32_16x16x32_bf16 v[64:67], v[178:181], v[214:217], v[64:67]
	v_mfma_f32_16x16x32_bf16 v[116:119], v[174:177], v[190:193], v[116:119]
	v_mfma_f32_16x16x32_bf16 v[112:115], v[182:185], v[190:193], v[112:115]
	v_mfma_f32_16x16x32_bf16 v[100:103], v[174:177], v[202:205], v[100:103]
	v_mfma_f32_16x16x32_bf16 v[96:99], v[182:185], v[202:205], v[96:99]
	v_mfma_f32_16x16x32_bf16 v[84:87], v[174:177], v[210:213], v[84:87]
	v_mfma_f32_16x16x32_bf16 v[80:83], v[182:185], v[210:213], v[80:83]
	v_mfma_f32_16x16x32_bf16 v[68:71], v[174:177], v[218:221], v[68:71]
	v_mfma_f32_16x16x32_bf16 v[64:67], v[182:185], v[218:221], v[64:67]
	s_setprio 0
	s_barrier
	s_add_i32 s30, s60, s3
	v_lshl_add_u64 v[148:149], s[42:43], 0, v[132:133]
	s_mov_b32 m0, s30
	ds_read_b128 v[186:189], v156 offset:16384
	ds_read_b128 v[190:193], v156 offset:17408
	ds_read_b128 v[198:201], v156 offset:18432
	ds_read_b128 v[202:205], v156 offset:19456
	ds_read_b128 v[206:209], v156 offset:20480
	ds_read_b128 v[210:213], v156 offset:21504
	ds_read_b128 v[214:217], v156 offset:22528
	ds_read_b128 v[218:221], v156 offset:23552
	global_load_lds_dwordx4 v[148:149], off
	s_add_i32 m0, s30, 0x2000
	s_add_u32 s30, s42, 0xb0000
	v_lshl_add_u64 v[194:195], s[42:43], 0, v[128:129]
	s_addc_u32 s31, s43, 0
	s_add_i32 s46, s61, s3
	global_load_lds_dwordx4 v[194:195], off
	v_lshl_add_u64 v[196:197], s[30:31], 0, v[132:133]
	s_mov_b32 m0, s46
	v_lshl_add_u64 v[222:223], s[52:53], 0, v[130:131]
	global_load_lds_dwordx4 v[196:197], off
	v_lshl_add_u64 v[196:197], s[30:31], 0, v[128:129]
	s_add_i32 m0, s46, 0x2000
	s_nop 0
	global_load_lds_dwordx4 v[196:197], off
	v_lshl_add_u64 v[196:197], s[52:53], 0, v[134:135]
	s_mov_b32 m0, s50
	s_nop 0
	global_load_lds_dwordx4 v[196:197], off
	s_mov_b32 m0, s51
	s_nop 0
	global_load_lds_dwordx4 v[222:223], off
	s_nop 0
	s_waitcnt vmcnt(8)
	s_waitcnt lgkmcnt(0)
	s_barrier
	s_setprio 1
	s_waitcnt lgkmcnt(0)
	v_mfma_f32_16x16x32_bf16 v[60:63], v[144:147], v[186:189], v[60:63]
	v_mfma_f32_16x16x32_bf16 v[56:59], v[162:165], v[186:189], v[56:59]
	v_mfma_f32_16x16x32_bf16 v[44:47], v[144:147], v[198:201], v[44:47]
	v_mfma_f32_16x16x32_bf16 v[40:43], v[162:165], v[198:201], v[40:43]
	v_mfma_f32_16x16x32_bf16 v[28:31], v[144:147], v[206:209], v[28:31]
	v_mfma_f32_16x16x32_bf16 v[24:27], v[162:165], v[206:209], v[24:27]
	v_mfma_f32_16x16x32_bf16 v[12:15], v[144:147], v[214:217], v[12:15]
	v_mfma_f32_16x16x32_bf16 v[8:11], v[162:165], v[214:217], v[8:11]
	v_mfma_f32_16x16x32_bf16 v[60:63], v[158:161], v[190:193], v[60:63]
	v_mfma_f32_16x16x32_bf16 v[56:59], v[166:169], v[190:193], v[56:59]
	v_mfma_f32_16x16x32_bf16 v[44:47], v[158:161], v[202:205], v[44:47]
	v_mfma_f32_16x16x32_bf16 v[40:43], v[166:169], v[202:205], v[40:43]
	v_mfma_f32_16x16x32_bf16 v[28:31], v[158:161], v[210:213], v[28:31]
	v_mfma_f32_16x16x32_bf16 v[24:27], v[166:169], v[210:213], v[24:27]
	v_mfma_f32_16x16x32_bf16 v[12:15], v[158:161], v[218:221], v[12:15]
	v_mfma_f32_16x16x32_bf16 v[8:11], v[166:169], v[218:221], v[8:11]
	s_setprio 0
	s_setprio 1
	v_mfma_f32_16x16x32_bf16 v[52:55], v[170:173], v[186:189], v[52:55]
	v_mfma_f32_16x16x32_bf16 v[48:51], v[178:181], v[186:189], v[48:51]
	v_mfma_f32_16x16x32_bf16 v[36:39], v[170:173], v[198:201], v[36:39]
	v_mfma_f32_16x16x32_bf16 v[32:35], v[178:181], v[198:201], v[32:35]
	v_mfma_f32_16x16x32_bf16 v[20:23], v[170:173], v[206:209], v[20:23]
	v_mfma_f32_16x16x32_bf16 v[16:19], v[178:181], v[206:209], v[16:19]
	v_mfma_f32_16x16x32_bf16 v[4:7], v[170:173], v[214:217], v[4:7]
	v_mfma_f32_16x16x32_bf16 v[0:3], v[178:181], v[214:217], v[0:3]
	v_mfma_f32_16x16x32_bf16 v[52:55], v[174:177], v[190:193], v[52:55]
	v_mfma_f32_16x16x32_bf16 v[48:51], v[182:185], v[190:193], v[48:51]
	v_mfma_f32_16x16x32_bf16 v[36:39], v[174:177], v[202:205], v[36:39]
	v_mfma_f32_16x16x32_bf16 v[32:35], v[182:185], v[202:205], v[32:35]
	v_mfma_f32_16x16x32_bf16 v[20:23], v[174:177], v[210:213], v[20:23]
	v_mfma_f32_16x16x32_bf16 v[16:19], v[182:185], v[210:213], v[16:19]
	v_mfma_f32_16x16x32_bf16 v[4:7], v[174:177], v[218:221], v[4:7]
	v_mfma_f32_16x16x32_bf16 v[0:3], v[182:185], v[218:221], v[0:3]
	s_setprio 0
	s_barrier
	s_add_i32 s46, 0, 0x18000
	v_add_u32_e32 v157, s46, v152
	s_add_i32 s47, 0, 0x1c000
	ds_read_b128 v[144:147], v157
	ds_read_b128 v[158:161], v157 offset:1024
	ds_read_b128 v[162:165], v157 offset:2048
	ds_read_b128 v[166:169], v157 offset:3072
	v_add_u32_e32 v157, s47, v152
	ds_read_b128 v[170:173], v157
	ds_read_b128 v[174:177], v157 offset:1024
	ds_read_b128 v[178:181], v157 offset:2048
	ds_read_b128 v[182:185], v157 offset:3072
	s_add_u32 s30, s52, 0xb0000
	s_addc_u32 s31, s53, 0
	s_mov_b32 m0, s54
	v_lshl_add_u64 v[224:225], s[30:31], 0, v[134:135]
	ds_read_b128 v[186:189], v156 offset:32768
	ds_read_b128 v[190:193], v156 offset:33792
	ds_read_b128 v[198:201], v156 offset:34816
	ds_read_b128 v[202:205], v156 offset:35840
	ds_read_b128 v[206:209], v156 offset:36864
	ds_read_b128 v[210:213], v156 offset:37888
	ds_read_b128 v[214:217], v156 offset:38912
	ds_read_b128 v[218:221], v156 offset:39936
	global_load_lds_dwordx4 v[224:225], off
	v_lshl_add_u64 v[224:225], s[30:31], 0, v[130:131]
	s_mov_b32 m0, s55
	s_nop 0
	global_load_lds_dwordx4 v[224:225], off
	s_nop 0
	s_waitcnt vmcnt(8)
	s_waitcnt lgkmcnt(0)
	s_barrier
	s_setprio 1
	s_waitcnt lgkmcnt(0)
	v_mfma_f32_16x16x32_bf16 v[124:127], v[144:147], v[186:189], v[124:127]
	v_mfma_f32_16x16x32_bf16 v[120:123], v[162:165], v[186:189], v[120:123]
	v_mfma_f32_16x16x32_bf16 v[108:111], v[144:147], v[198:201], v[108:111]
	v_mfma_f32_16x16x32_bf16 v[104:107], v[162:165], v[198:201], v[104:107]
	v_mfma_f32_16x16x32_bf16 v[92:95], v[144:147], v[206:209], v[92:95]
	v_mfma_f32_16x16x32_bf16 v[88:91], v[162:165], v[206:209], v[88:91]
	v_mfma_f32_16x16x32_bf16 v[76:79], v[144:147], v[214:217], v[76:79]
	v_mfma_f32_16x16x32_bf16 v[72:75], v[162:165], v[214:217], v[72:75]
	v_mfma_f32_16x16x32_bf16 v[124:127], v[158:161], v[190:193], v[124:127]
	v_mfma_f32_16x16x32_bf16 v[120:123], v[166:169], v[190:193], v[120:123]
	v_mfma_f32_16x16x32_bf16 v[108:111], v[158:161], v[202:205], v[108:111]
	v_mfma_f32_16x16x32_bf16 v[104:107], v[166:169], v[202:205], v[104:107]
	v_mfma_f32_16x16x32_bf16 v[92:95], v[158:161], v[210:213], v[92:95]
	v_mfma_f32_16x16x32_bf16 v[88:91], v[166:169], v[210:213], v[88:91]
	v_mfma_f32_16x16x32_bf16 v[76:79], v[158:161], v[218:221], v[76:79]
	v_mfma_f32_16x16x32_bf16 v[72:75], v[166:169], v[218:221], v[72:75]
	s_setprio 0
	s_setprio 1
	v_mfma_f32_16x16x32_bf16 v[116:119], v[170:173], v[186:189], v[116:119]
	v_mfma_f32_16x16x32_bf16 v[112:115], v[178:181], v[186:189], v[112:115]
	v_mfma_f32_16x16x32_bf16 v[100:103], v[170:173], v[198:201], v[100:103]
	v_mfma_f32_16x16x32_bf16 v[96:99], v[178:181], v[198:201], v[96:99]
	v_mfma_f32_16x16x32_bf16 v[84:87], v[170:173], v[206:209], v[84:87]
	v_mfma_f32_16x16x32_bf16 v[80:83], v[178:181], v[206:209], v[80:83]
	v_mfma_f32_16x16x32_bf16 v[68:71], v[170:173], v[214:217], v[68:71]
	v_mfma_f32_16x16x32_bf16 v[64:67], v[178:181], v[214:217], v[64:67]
	v_mfma_f32_16x16x32_bf16 v[116:119], v[174:177], v[190:193], v[116:119]
	v_mfma_f32_16x16x32_bf16 v[112:115], v[182:185], v[190:193], v[112:115]
	v_mfma_f32_16x16x32_bf16 v[100:103], v[174:177], v[202:205], v[100:103]
	v_mfma_f32_16x16x32_bf16 v[96:99], v[182:185], v[202:205], v[96:99]
	v_mfma_f32_16x16x32_bf16 v[84:87], v[174:177], v[210:213], v[84:87]
	v_mfma_f32_16x16x32_bf16 v[80:83], v[182:185], v[210:213], v[80:83]
	v_mfma_f32_16x16x32_bf16 v[68:71], v[174:177], v[218:221], v[68:71]
	v_mfma_f32_16x16x32_bf16 v[64:67], v[182:185], v[218:221], v[64:67]
	s_setprio 0
	s_barrier
	s_add_i32 s30, s46, s3
	v_lshl_add_u64 v[148:149], v[148:149], 0, s[16:17]
	s_mov_b32 m0, s30
	ds_read_b128 v[186:189], v156 offset:49152
	ds_read_b128 v[190:193], v156 offset:50176
	ds_read_b128 v[198:201], v156 offset:51200
	ds_read_b128 v[202:205], v156 offset:52224
	ds_read_b128 v[206:209], v156 offset:53248
	ds_read_b128 v[210:213], v156 offset:54272
	ds_read_b128 v[214:217], v156 offset:55296
	ds_read_b128 v[218:221], v156 offset:56320
	global_load_lds_dwordx4 v[148:149], off
	s_add_i32 m0, s30, 0x2000
	s_add_u32 s30, s42, 0xb0080
	v_lshl_add_u64 v[148:149], v[194:195], 0, s[16:17]
	s_addc_u32 s31, s43, 0
	s_add_i32 s42, s47, s3
	global_load_lds_dwordx4 v[148:149], off
	v_lshl_add_u64 v[148:149], s[30:31], 0, v[132:133]
	s_mov_b32 m0, s42
	s_nop 0
	global_load_lds_dwordx4 v[148:149], off
	v_lshl_add_u64 v[148:149], s[30:31], 0, v[128:129]
	s_add_i32 m0, s42, 0x2000
	s_nop 0
	global_load_lds_dwordx4 v[148:149], off
	v_lshl_add_u64 v[148:149], v[196:197], 0, s[16:17]
	s_mov_b32 m0, s57
	s_nop 0
	global_load_lds_dwordx4 v[148:149], off
	v_lshl_add_u64 v[148:149], v[222:223], 0, s[16:17]
	s_mov_b32 m0, s58
	s_nop 0
	global_load_lds_dwordx4 v[148:149], off
	s_waitcnt vmcnt(8)
	s_waitcnt lgkmcnt(0)
	s_barrier
	s_setprio 1
	s_waitcnt lgkmcnt(0)
	v_mfma_f32_16x16x32_bf16 v[60:63], v[144:147], v[186:189], v[60:63]
	v_mfma_f32_16x16x32_bf16 v[56:59], v[162:165], v[186:189], v[56:59]
	v_mfma_f32_16x16x32_bf16 v[44:47], v[144:147], v[198:201], v[44:47]
	v_mfma_f32_16x16x32_bf16 v[40:43], v[162:165], v[198:201], v[40:43]
	v_mfma_f32_16x16x32_bf16 v[28:31], v[144:147], v[206:209], v[28:31]
	v_mfma_f32_16x16x32_bf16 v[24:27], v[162:165], v[206:209], v[24:27]
	v_mfma_f32_16x16x32_bf16 v[12:15], v[144:147], v[214:217], v[12:15]
	v_mfma_f32_16x16x32_bf16 v[8:11], v[162:165], v[214:217], v[8:11]
	v_mfma_f32_16x16x32_bf16 v[60:63], v[158:161], v[190:193], v[60:63]
	v_mfma_f32_16x16x32_bf16 v[56:59], v[166:169], v[190:193], v[56:59]
	v_mfma_f32_16x16x32_bf16 v[44:47], v[158:161], v[202:205], v[44:47]
	v_mfma_f32_16x16x32_bf16 v[40:43], v[166:169], v[202:205], v[40:43]
	v_mfma_f32_16x16x32_bf16 v[28:31], v[158:161], v[210:213], v[28:31]
	v_mfma_f32_16x16x32_bf16 v[24:27], v[166:169], v[210:213], v[24:27]
	v_mfma_f32_16x16x32_bf16 v[12:15], v[158:161], v[218:221], v[12:15]
	v_mfma_f32_16x16x32_bf16 v[8:11], v[166:169], v[218:221], v[8:11]
	s_setprio 0
	s_setprio 1
	v_mfma_f32_16x16x32_bf16 v[52:55], v[170:173], v[186:189], v[52:55]
	v_mfma_f32_16x16x32_bf16 v[48:51], v[178:181], v[186:189], v[48:51]
	v_mfma_f32_16x16x32_bf16 v[36:39], v[170:173], v[198:201], v[36:39]
	v_mfma_f32_16x16x32_bf16 v[32:35], v[178:181], v[198:201], v[32:35]
	v_mfma_f32_16x16x32_bf16 v[20:23], v[170:173], v[206:209], v[20:23]
	v_mfma_f32_16x16x32_bf16 v[16:19], v[178:181], v[206:209], v[16:19]
	v_mfma_f32_16x16x32_bf16 v[4:7], v[170:173], v[214:217], v[4:7]
	v_mfma_f32_16x16x32_bf16 v[0:3], v[178:181], v[214:217], v[0:3]
	v_mfma_f32_16x16x32_bf16 v[52:55], v[174:177], v[190:193], v[52:55]
	v_mfma_f32_16x16x32_bf16 v[48:51], v[182:185], v[190:193], v[48:51]
	v_mfma_f32_16x16x32_bf16 v[36:39], v[174:177], v[202:205], v[36:39]
	v_mfma_f32_16x16x32_bf16 v[32:35], v[182:185], v[202:205], v[32:35]
	v_mfma_f32_16x16x32_bf16 v[20:23], v[174:177], v[210:213], v[20:23]
	v_mfma_f32_16x16x32_bf16 v[16:19], v[182:185], v[210:213], v[16:19]
	v_mfma_f32_16x16x32_bf16 v[4:7], v[174:177], v[218:221], v[4:7]
	v_mfma_f32_16x16x32_bf16 v[0:3], v[182:185], v[218:221], v[0:3]
	s_setprio 0
	s_barrier
	s_add_i32 s67, s67, 2
	s_add_u32 s65, s65, 0x100
	s_addc_u32 s66, s66, 0
	s_cmp_gt_u32 s67, 41
	s_mov_b64 s[30:31], s[40:41]
	s_cbranch_scc0 .LBB0_1584
	s_and_b64 vcc, exec, s[18:19]
	s_cbranch_vccz .LBB0_1587
	s_barrier
